# stick-breaking: tiles entirely below the rows of a wave run a copy of the tile block without the 32 causal tests and 64 selects
# speedup vs baseline: 1.0106x; 1.0015x over previous
.LBB0_465:
	s_cmp_ge_i32 s23, s4
	s_cselect_b64 s[16:17], -1, 0
	s_or_b64 s[16:17], s[16:17], s[14:15]
	s_and_b64 vcc, exec, s[16:17]
	s_cbranch_vccnz .LBB0_467
	s_add_i32 s98, s23, 94
	s_cmp_lt_i32 s98, s4
	s_cbranch_scc0 .Lsb_near
	v_add3_u32 v130, s18, v192, v205
	ds_read_b128 v[64:67], v130 offset:8704
	ds_read_b128 v[132:135], v130 offset:8736
	v_add3_u32 v207, s22, v204, v206
	s_waitcnt lgkmcnt(1)
	v_mfma_f32_32x32x16_bf16 v[66:81], v[64:67], v[82:85], 0
	s_waitcnt lgkmcnt(0)
	v_mfma_f32_32x32x16_bf16 v[66:81], v[132:135], v[86:89], v[66:81]
	ds_read_b128 v[132:135], v130 offset:8768
	ds_read_b128 v[136:139], v130 offset:8800
	s_waitcnt lgkmcnt(1)
	v_mfma_f32_32x32x16_bf16 v[66:81], v[132:135], v[90:93], v[66:81]
	s_waitcnt lgkmcnt(0)
	v_mfma_f32_32x32x16_bf16 v[66:81], v[136:139], v[94:97], v[66:81]
	ds_read_b128 v[132:135], v130 offset:8832
	ds_read_b128 v[136:139], v130 offset:8864
	s_waitcnt lgkmcnt(1)
	v_mfma_f32_32x32x16_bf16 v[66:81], v[132:135], v[98:101], v[66:81]
	s_waitcnt lgkmcnt(0)
	v_mfma_f32_32x32x16_bf16 v[66:81], v[136:139], v[102:105], v[66:81]
	ds_read_b128 v[132:135], v130 offset:8896
	ds_read_b128 v[136:139], v130 offset:8928
	ds_read_b128 v[208:211], v130 offset:224
	s_waitcnt lgkmcnt(2)
	v_mfma_f32_32x32x16_bf16 v[66:81], v[132:135], v[106:109], v[66:81]
	s_waitcnt lgkmcnt(1)
	v_mfma_f32_32x32x16_bf16 v[66:81], v[136:139], v[110:113], v[66:81]
	s_nop 11
	v_mov_b32_e32 v64, v66
	v_mov_b32_e32 v65, v68
	v_mov_b32_e32 v68, v67
	v_mul_f32_e32 v132, s68, v64
	v_mul_f32_e32 v133, s68, v65
	v_mov_b32_e32 v66, v70
	v_mul_f32_e32 v134, s68, v68
	v_mul_f32_e32 v135, s68, v69
	v_mul_f32_e64 v70, |v132|, s54
	v_mov_b32_e32 v67, v72
	v_mul_f32_e64 v72, |v134|, s54
	v_exp_f32_e32 v70, v70
	v_mul_f32_e64 v131, |v133|, s54
	v_exp_f32_e32 v72, v72
	v_mul_f32_e64 v138, |v135|, s54
	v_exp_f32_e32 v131, v131
	v_mul_f32_e32 v136, s68, v66
	v_mul_f32_e32 v137, s68, v67
	v_exp_f32_e32 v138, v138
	v_mul_f32_e64 v139, |v136|, s54
	v_add_f32_e32 v70, 1.0, v70
	v_exp_f32_e32 v139, v139
	v_add_f32_e32 v72, 1.0, v72
	v_add_f32_e32 v131, 1.0, v131
	v_add_f32_e32 v138, 1.0, v138
	v_log_f32_e32 v70, v70
	v_add_f32_e32 v139, 1.0, v139
	v_log_f32_e32 v72, v72
	v_log_f32_e32 v131, v131
	v_log_f32_e32 v138, v138
	v_mov_b32_e32 v142, v139
	v_mul_f32_e32 v139, 0x3f317217, v70
	v_mul_f32_e32 v140, 0x3f317217, v72
	v_fma_f32 v139, v70, s86, -v139
	v_mul_f32_e32 v141, 0x3f317217, v131
	v_fma_f32 v140, v72, s86, -v140
	v_fmac_f32_e32 v139, 0x3377d1cf, v70
	v_mul_f32_e32 v143, 0x3f317217, v138
	v_fma_f32 v141, v131, s86, -v141
	v_fmac_f32_e32 v140, 0x3377d1cf, v72
	v_fmac_f32_e32 v139, 0x3f317217, v70
	v_fma_f32 v143, v138, s86, -v143
	v_fmac_f32_e32 v141, 0x3377d1cf, v131
	v_fmac_f32_e32 v140, 0x3f317217, v72
	v_fmac_f32_e32 v143, 0x3377d1cf, v138
	v_fmac_f32_e32 v141, 0x3f317217, v131
	v_fmac_f32_e32 v143, 0x3f317217, v138
	v_min_f32_e32 v132, 0, v132
	v_min_f32_e32 v133, 0, v133
	v_sub_f32_e32 v166, v132, v139
	v_sub_f32_e32 v167, v133, v141
	v_fma_f32 v174, -v64, s68, v166
	v_fma_f32 v175, -v65, s68, v167
	v_log_f32_e32 v65, v142
	v_min_f32_e32 v134, 0, v134
	v_min_f32_e32 v135, 0, v135
	v_sub_f32_e32 v164, v134, v140
	v_sub_f32_e32 v165, v135, v143
	v_mov_b32_e32 v72, v71
	v_fma_f32 v172, -v68, s68, v164
	v_fma_f32 v173, -v69, s68, v165
	v_mul_f32_e32 v68, 0x3f317217, v65
	v_fma_f32 v70, v65, s86, -v68
	v_mul_f32_e32 v68, s68, v72
	v_mul_f32_e32 v69, s68, v73
	v_fmac_f32_e32 v70, 0x3377d1cf, v65
	v_mul_f32_e64 v71, |v68|, s54
	v_exp_f32_e32 v71, v71
	v_fmac_f32_e32 v70, 0x3f317217, v65
	v_mul_f32_e64 v131, |v137|, s54
	v_exp_f32_e32 v131, v131
	v_mov_b32_e32 v65, v70
	v_add_f32_e32 v70, 1.0, v71
	v_mul_f32_e64 v133, |v69|, s54
	v_exp_f32_e32 v133, v133
	v_log_f32_e32 v71, v70
	v_mov_b32_e32 v70, v65
	v_min_f32_e32 v64, 0, v136
	v_mul_f32_e32 v65, 0x3f317217, v71
	v_fma_f32 v65, v71, s86, -v65
	v_fmac_f32_e32 v65, 0x3377d1cf, v71
	v_fmac_f32_e32 v65, 0x3f317217, v71
	v_min_f32_e32 v68, 0, v68
	v_min_f32_e32 v69, 0, v69
	v_add_f32_e32 v71, 1.0, v131
	v_mov_b32_e32 v140, v78
	v_mov_b32_e32 v141, v80
	v_log_f32_e32 v71, v71
	v_mov_b32_e32 v132, v65
	v_min_f32_e32 v65, 0, v137
	v_mul_f32_e32 v131, 0x3f317217, v71
	v_fma_f32 v131, v71, s86, -v131
	v_fmac_f32_e32 v131, 0x3377d1cf, v71
	v_fmac_f32_e32 v131, 0x3f317217, v71
	v_mul_f32_e32 v142, s68, v140
	v_mul_f32_e32 v143, s68, v141
	v_mov_b32_e32 v80, v79
	v_mov_b32_e32 v71, v131
	v_add_f32_e32 v131, 1.0, v133
	v_sub_f32_e32 v168, v64, v70
	v_sub_f32_e32 v169, v65, v71
	v_log_f32_e32 v131, v131
	v_fma_f32 v176, -v66, s68, v168
	v_fma_f32 v177, -v67, s68, v169
	v_mul_f32_e32 v144, s68, v80
	v_mul_f32_e32 v145, s68, v81
	v_mul_f32_e32 v64, 0x3f317217, v131
	v_fma_f32 v70, v131, s86, -v64
	v_mov_b32_e32 v64, v74
	v_mul_f32_e32 v66, s68, v64
	v_mul_f32_e32 v67, s68, v76
	v_fmac_f32_e32 v70, 0x3377d1cf, v131
	v_mul_f32_e64 v71, |v66|, s54
	v_exp_f32_e32 v71, v71
	v_fmac_f32_e32 v70, 0x3f317217, v131
	v_min_f32_e32 v66, 0, v66
	v_mov_b32_e32 v133, v70
	v_add_f32_e32 v70, 1.0, v71
	v_sub_f32_e32 v170, v68, v132
	v_sub_f32_e32 v171, v69, v133
	ds_read_b128 v[132:135], v130 offset:32
	v_log_f32_e32 v70, v70
	v_fma_f32 v178, -v72, s68, v170
	v_fma_f32 v179, -v73, s68, v171
	v_mul_f32_e64 v73, |v67|, s54
	v_exp_f32_e32 v73, v73
	v_mul_f32_e32 v68, 0x3f317217, v70
	v_fma_f32 v71, v70, s86, -v68
	v_mul_f32_e32 v68, s68, v75
	v_mul_f32_e32 v69, s68, v77
	v_fmac_f32_e32 v71, 0x3377d1cf, v70
	v_mul_f32_e64 v72, |v68|, s54
	v_exp_f32_e32 v72, v72
	v_fmac_f32_e32 v71, 0x3f317217, v70
	v_mul_f32_e64 v74, |v69|, s54
	v_exp_f32_e32 v74, v74
	v_mov_b32_e32 v70, v71
	v_add_f32_e32 v71, 1.0, v72
	v_min_f32_e32 v67, 0, v67
	v_min_f32_e32 v68, 0, v68
	v_log_f32_e32 v71, v71
	v_mov_b32_e32 v70, v70
	v_min_f32_e32 v69, 0, v69
	v_mul_f32_e32 v72, 0x3f317217, v71
	v_fma_f32 v72, v71, s86, -v72
	v_fmac_f32_e32 v72, 0x3377d1cf, v71
	v_fmac_f32_e32 v72, 0x3f317217, v71
	s_nop 1
	v_mov_b32_e32 v71, v72
	v_add_f32_e32 v72, 1.0, v73
	s_nop 1
	v_log_f32_e32 v73, v72
	v_mov_b32_e32 v72, v71
	v_mul_f32_e32 v71, 0x3f317217, v73
	v_fma_f32 v71, v73, s86, -v71
	v_fmac_f32_e32 v71, 0x3377d1cf, v73
	v_fmac_f32_e32 v71, 0x3f317217, v73
	s_nop 1
	v_add_f32_e32 v73, 1.0, v74
	v_sub_f32_e32 v180, v66, v70
	v_sub_f32_e32 v181, v67, v71
	v_mul_f32_e64 v70, |v143|, s54
	v_log_f32_e32 v73, v73
	v_fma_f32 v184, -v64, s68, v180
	v_fma_f32 v185, -v76, s68, v181
	v_mul_f32_e64 v65, |v142|, s54
	v_exp_f32_e32 v65, v65
	v_mul_f32_e32 v64, 0x3f317217, v73
	v_fma_f32 v64, v73, s86, -v64
	v_fmac_f32_e32 v64, 0x3377d1cf, v73
	v_fmac_f32_e32 v64, 0x3f317217, v73
	v_exp_f32_e32 v131, v70
	v_mov_b32_e32 v73, v64
	v_add_f32_e32 v64, 1.0, v65
	v_mul_f32_e64 v66, |v144|, s54
	v_exp_f32_e32 v66, v66
	v_log_f32_e32 v64, v64
	v_sub_f32_e32 v182, v68, v72
	v_sub_f32_e32 v183, v69, v73
	v_add_f32_e32 v131, 1.0, v131
	v_fma_f32 v186, -v75, s68, v182
	v_fma_f32 v187, -v77, s68, v183
	v_mul_f32_e32 v65, 0x3f317217, v64
	v_fma_f32 v65, v64, s86, -v65
	v_fmac_f32_e32 v65, 0x3377d1cf, v64
	v_fmac_f32_e32 v65, 0x3f317217, v64
	v_min_f32_e32 v142, 0, v142
	v_min_f32_e32 v143, 0, v143
	v_mov_b32_e32 v64, v65
	v_add_f32_e32 v65, 1.0, v66
	v_min_f32_e32 v144, 0, v144
	v_log_f32_e32 v68, v65
	v_mov_b32_e32 v146, v64
	ds_read_b128 v[64:67], v130
	v_mul_f32_e32 v69, 0x3f317217, v68
	v_fma_f32 v69, v68, s86, -v69
	v_fmac_f32_e32 v69, 0x3377d1cf, v68
	v_fmac_f32_e32 v69, 0x3f317217, v68
	s_nop 0
	v_mov_b32_e32 v147, v69
	s_waitcnt lgkmcnt(0)
	v_mfma_f32_32x32x16_bf16 v[64:79], v[64:67], v[82:85], 0
	v_mov_b32_e32 v148, v147
	s_nop 0
	ds_read_b128 v[136:139], v130 offset:64
	v_log_f32_e32 v131, v131
	v_mfma_f32_32x32x16_bf16 v[64:79], v[132:135], v[86:89], v[64:79]
	v_mul_f32_e32 v132, 0x3f317217, v131
	v_fma_f32 v147, v131, s86, -v132
	ds_read_b128 v[132:135], v130 offset:96
	v_fmac_f32_e32 v147, 0x3377d1cf, v131
	v_fmac_f32_e32 v147, 0x3f317217, v131
	s_waitcnt lgkmcnt(1)
	v_mfma_f32_32x32x16_bf16 v[64:79], v[136:139], v[90:93], v[64:79]
	v_mul_f32_e64 v137, |v145|, s54
	v_exp_f32_e32 v149, v137
	ds_read_b128 v[136:139], v130 offset:128
	s_waitcnt lgkmcnt(1)
	v_mfma_f32_32x32x16_bf16 v[64:79], v[132:135], v[94:97], v[64:79]
	v_add_f32_e32 v131, 1.0, v149
	v_add_f32_e64 v188, v142, -v146
	v_add_f32_e64 v189, v143, -v147
	v_min_f32_e32 v145, 0, v145
	ds_read_b128 v[132:135], v130 offset:160
	s_waitcnt lgkmcnt(1)
	v_mfma_f32_32x32x16_bf16 v[64:79], v[136:139], v[98:101], v[64:79]
	v_log_f32_e32 v131, v131
	v_fma_f32 v212, -v140, s68, v188
	v_fma_f32 v213, -v141, s68, v189
	v_mul_f32_e32 v136, 0x3f317217, v131
	v_fma_f32 v140, v131, s86, -v136
	ds_read_b128 v[136:139], v130 offset:192
	s_waitcnt lgkmcnt(1)
	v_mfma_f32_32x32x16_bf16 v[64:79], v[132:135], v[102:105], v[64:79]
	v_fmac_f32_e32 v140, 0x3377d1cf, v131
	v_fmac_f32_e32 v140, 0x3f317217, v131
	s_nop 0
	s_waitcnt lgkmcnt(0)
	v_mfma_f32_32x32x16_bf16 v[64:79], v[136:139], v[106:109], v[64:79]
	v_add_f32_e64 v190, v144, -v148
	v_add_f32_e64 v191, v145, -v140
	ds_read_b64_tr_b16 v[146:147], v207 offset:45056
	ds_read_b64_tr_b16 v[142:143], v207 offset:45120
	ds_read_b64_tr_b16 v[138:139], v207 offset:45184
	ds_read_b64_tr_b16 v[134:135], v207 offset:45248
	ds_read_b64_tr_b16 v[148:149], v207 offset:47616
	ds_read_b64_tr_b16 v[144:145], v207 offset:47680
	ds_read_b64_tr_b16 v[140:141], v207 offset:47744
	ds_read_b64_tr_b16 v[136:137], v207 offset:47808
	ds_read_b64_tr_b16 v[130:131], v207 offset:50176
	ds_read_b64_tr_b16 v[132:133], v207 offset:52736
	v_fma_f32 v216, -v80, s68, v190
	v_fma_f32 v217, -v81, s68, v191
	v_mfma_f32_32x32x16_bf16 v[64:79], v[208:211], v[110:113], v[64:79]
	v_mov_b32_e32 v80, v174
	v_mov_b32_e32 v81, v175
	v_mov_b32_e32 v174, v172
	v_mov_b32_e32 v175, v173
	v_add_f32_e32 v80, v80, v174
	v_add_f32_e32 v81, v81, v175
	v_add_f32_e32 v172, v80, v81
	v_add_f32_e32 v173, v81, v80
	v_mov_b32_e32 v210, v216
	v_add_f32_e32 v184, v184, v186
	v_add_f32_e32 v185, v185, v187
	v_add_f32_e32 v208, v212, v210
	v_add_f32_e32 v209, v213, v217
	v_add_f32_e32 v240, v184, v185
	v_add_f32_e32 v241, v185, v184
	v_add_f32_e32 v212, v208, v209
	v_add_f32_e32 v213, v209, v208
	ds_bpermute_b32 v216, v235, v212
	ds_bpermute_b32 v184, v235, v240
	s_waitcnt lgkmcnt(1)
	v_add_f32_e32 v208, v212, v216
	s_waitcnt lgkmcnt(0)
	v_cndmask_b32_e64 v213, 0, v184, s[10:11]
	v_add_f32_e32 v208, v213, v208
	v_add_f32_e32 v245, v162, v208
	v_add_f32_e32 v246, v186, v185
	v_add_f32_e32 v247, v180, v245
	v_add_f32_e32 v182, v182, v245
	v_add_f32_e32 v180, v246, v247
	v_mul_f32_e32 v180, 0x3fb8aa3b, v180
	v_exp_f32_e32 v180, v180
	v_add_f32_e32 v182, v185, v182
	v_mul_f32_e32 v182, 0x3fb8aa3b, v182
	v_exp_f32_e32 v182, v182
	v_add_f32_e32 v176, v176, v178
	v_add_f32_e32 v177, v177, v179
	v_mov_b32_e32 v213, v180
	v_add_f32_e32 v180, v181, v245
	v_add_f32_e32 v242, v176, v177
	v_add_f32_e32 v243, v177, v176
	v_add_f32_e32 v180, v187, v180
	ds_bpermute_b32 v80, v235, v172
	ds_bpermute_b32 v176, v235, v242
	v_mul_f32_e32 v180, 0x3fb8aa3b, v180
	v_mov_b32_e32 v215, v182
	v_exp_f32_e32 v239, v180
	v_add_f32_e32 v180, v183, v245
	v_add_f32_e32 v182, v184, v216
	v_add_f32_e32 v183, v240, v212
	v_add_f32_e32 v180, 0, v180
	v_add_f32_e32 v181, v242, v183
	v_add_f32_e32 v181, v181, v216
	v_add_f32_e32 v181, v181, v184
	v_cndmask_b32_e64 v173, 0, v216, s[10:11]
	s_waitcnt lgkmcnt(1)
	v_cndmask_b32_e64 v208, 0, v80, s[10:11]
	v_mul_f32_e32 v180, 0x3fb8aa3b, v180
	s_waitcnt lgkmcnt(0)
	v_add_f32_e32 v181, v181, v176
	v_exp_f32_e32 v241, v180
	v_add_f32_e32 v180, v162, v173
	v_add_f32_e32 v173, v183, v216
	v_add_f32_e32 v181, v208, v181
	v_cndmask_b32_e64 v186, 0, v176, s[10:11]
	v_add_f32_e32 v173, v173, v184
	v_add_f32_e32 v185, v162, v181
	v_add_f32_e32 v173, v186, v173
	v_add_f32_e32 v164, v164, v185
	v_add_f32_e32 v186, v174, v81
	v_add_f32_e32 v187, v166, v185
	v_add_f32_e32 v81, v81, v164
	v_add_f32_e32 v164, v167, v185
	v_add_f32_e32 v165, v165, v185
	v_add_f32_e32 v166, v186, v187
	v_add_f32_e32 v164, v175, v164
	v_add_f32_e32 v165, 0, v165
	v_mul_f32_e32 v166, 0x3fb8aa3b, v166
	v_mul_f32_e32 v164, 0x3fb8aa3b, v164
	v_mul_f32_e32 v165, 0x3fb8aa3b, v165
	v_exp_f32_e32 v166, v166
	v_exp_f32_e32 v164, v164
	v_exp_f32_e32 v165, v165
	v_mov_b32_e32 v174, v166
	v_mov_b32_e32 v175, v164
	v_mov_b32_e32 v181, v165
	v_add_f32_e32 v165, v162, v173
	v_add_f32_e32 v166, v178, v177
	v_add_f32_e32 v167, v168, v165
	v_mul_f32_e32 v81, 0x3fb8aa3b, v81
	v_add_f32_e32 v164, v166, v167
	v_add_f32_e32 v166, v170, v165
	v_add_f32_e32 v167, v169, v165
	v_add_f32_e32 v165, v171, v165
	v_add_f32_e32 v166, v177, v166
	v_add_f32_e32 v167, v179, v167
	v_add_f32_e32 v165, 0, v165
	v_mul_f32_e32 v164, 0x3fb8aa3b, v164
	v_mul_f32_e32 v166, 0x3fb8aa3b, v166
	v_mul_f32_e32 v167, 0x3fb8aa3b, v167
	v_mul_f32_e32 v165, 0x3fb8aa3b, v165
	v_exp_f32_e32 v81, v81
	v_exp_f32_e32 v164, v164
	v_exp_f32_e32 v166, v166
	v_exp_f32_e32 v167, v167
	v_exp_f32_e32 v165, v165
	v_mov_b32_e32 v168, v164
	v_mov_b32_e32 v169, v165
	v_cvt_pk_bf16_f32 v164, v174, v81
	v_cvt_pk_bf16_f32 v165, v175, v181
	v_cvt_pk_bf16_f32 v166, v168, v166
	v_cvt_pk_bf16_f32 v167, v167, v169
	s_nop 0
	s_nop 0
	v_mfma_f32_32x32x16_bf16 v[48:63], v[146:149], v[164:167], v[48:63]
	v_add_f32_e64 v146, v180, v188
	v_add_f32_e64 v147, v210, v209
	v_add_f32_e32 v81, v146, v147
	v_mul_f32_e32 v81, 0x3fb8aa3b, v81
	v_exp_f32_e32 v81, v81
	v_mfma_f32_32x32x16_bf16 v[32:47], v[142:145], v[164:167], v[32:47]
	v_add_f32_e32 v143, v180, v190
	v_add_f32_e32 v144, v180, v189
	v_add_f32_e32 v143, v143, v209
	v_mul_f32_e32 v143, 0x3fb8aa3b, v143
	v_exp_f32_e32 v143, v143
	v_mfma_f32_32x32x16_bf16 v[16:31], v[138:141], v[164:167], v[16:31]
	v_add_f32_e32 v139, v180, v191
	v_add_f32_e32 v138, v144, v217
	v_add_f32_e32 v139, 0, v139
	v_mul_f32_e32 v138, 0x3fb8aa3b, v138
	v_mul_f32_e32 v139, 0x3fb8aa3b, v139
	v_exp_f32_e32 v138, v138
	v_exp_f32_e32 v139, v139
	v_mfma_f32_32x32x16_bf16 v[0:15], v[134:137], v[164:167], v[0:15]
	v_cvt_pk_bf16_f32 v134, v213, v215
	v_cvt_pk_bf16_f32 v135, v239, v241
	v_cvt_pk_bf16_f32 v136, v81, v143
	v_cvt_pk_bf16_f32 v137, v138, v139
	ds_read_b64_tr_b16 v[138:139], v207 offset:50240
	ds_read_b64_tr_b16 v[142:143], v207 offset:50304
	ds_read_b64_tr_b16 v[146:147], v207 offset:50368
	ds_read_b64_tr_b16 v[140:141], v207 offset:52800
	ds_read_b64_tr_b16 v[144:145], v207 offset:52864
	ds_read_b64_tr_b16 v[148:149], v207 offset:52928
	v_mfma_f32_32x32x16_bf16 v[48:63], v[130:133], v[134:137], v[48:63]
	v_mov_b32_e32 v130, v64
	v_mov_b32_e32 v131, v68
	v_mul_f32_e64 v132, v130, s68
	v_mul_f32_e64 v133, v131, s68
	v_mul_f32_e64 v64, |v132|, s54
	v_exp_f32_e32 v64, v64
	v_add_f32_e32 v80, v80, v176
	v_add_f32_e32 v81, v172, v242
	s_waitcnt lgkmcnt(2)
	v_mfma_f32_32x32x16_bf16 v[32:47], v[138:141], v[134:137], v[32:47]
	v_add_f32_e64 v80, v80, v182
	v_add_f32_e64 v81, v81, v183
	v_add_f32_e32 v64, 1.0, v64
	s_nop 1
	v_log_f32_e32 v138, v64
	v_min_f32_e32 v64, 0, v132
	s_waitcnt lgkmcnt(1)
	v_mfma_f32_32x32x16_bf16 v[16:31], v[142:145], v[134:137], v[16:31]
	v_mul_f32_e64 v143, |v133|, s54
	v_mul_f32_e32 v68, 0x3f317217, v138
	v_fma_f32 v132, v138, s86, -v68
	v_mov_b32_e32 v68, v65
	v_fmac_f32_e32 v132, 0x3377d1cf, v138
	v_fmac_f32_e32 v132, 0x3f317217, v138
	s_waitcnt lgkmcnt(0)
	v_mfma_f32_32x32x16_bf16 v[0:15], v[146:149], v[134:137], v[0:15]
	v_mul_f32_e64 v134, v68, s68
	v_mul_f32_e64 v135, v69, s68
	v_mul_f32_e64 v65, |v134|, s54
	v_exp_f32_e32 v65, v65
	v_mov_b32_e32 v137, v70
	v_exp_f32_e32 v143, v143
	v_min_f32_e32 v134, 0, v134
	v_add_f32_e32 v65, 1.0, v65
	v_add_f32_e32 v143, 1.0, v143
	s_nop 0
	v_log_f32_e32 v65, v65
	s_nop 0
	v_mul_f32_e32 v136, 0x3f317217, v65
	v_fma_f32 v140, v65, s86, -v136
	v_mov_b32_e32 v136, v66
	v_mul_f32_e32 v138, s68, v136
	v_mul_f32_e32 v139, s68, v137
	v_fmac_f32_e32 v140, 0x3377d1cf, v65
	v_mul_f32_e64 v66, |v138|, s54
	v_exp_f32_e32 v66, v66
	v_fmac_f32_e32 v140, 0x3f317217, v65
	v_min_f32_e32 v138, 0, v138
	v_add_f32_e32 v66, 1.0, v66
	v_mov_b32_e32 v65, v140
	s_nop 1
	v_log_f32_e32 v142, v66
	v_mov_b32_e32 v70, v67
	v_mul_f32_e32 v140, s68, v70
	v_mul_f32_e32 v141, s68, v71
	v_mul_f32_e64 v67, |v140|, s54
	v_exp_f32_e32 v67, v67
	v_mov_b32_e32 v66, v65
	v_mul_f32_e32 v65, 0x3f317217, v142
	v_fma_f32 v65, v142, s86, -v65
	v_fmac_f32_e32 v65, 0x3377d1cf, v142
	v_fmac_f32_e32 v65, 0x3f317217, v142
	v_add_f32_e32 v67, 1.0, v67
	v_min_f32_e32 v140, 0, v140
	s_nop 1
	v_log_f32_e32 v67, v67
	v_mov_b32_e32 v142, v65
	v_mul_f32_e32 v65, 0x3f317217, v67
	v_fma_f32 v65, v67, s86, -v65
	v_fmac_f32_e32 v65, 0x3377d1cf, v67
	v_fmac_f32_e32 v65, 0x3f317217, v67
	s_nop 1
	s_nop 0
	v_log_f32_e32 v143, v143
	v_mov_b32_e32 v144, v65
	v_min_f32_e32 v65, 0, v133
	v_mul_f32_e32 v133, 0x3f317217, v143
	v_fma_f32 v133, v143, s86, -v133
	v_fmac_f32_e32 v133, 0x3377d1cf, v143
	v_fmac_f32_e32 v133, 0x3f317217, v143
	s_nop 1
	v_sub_f32_e32 v64, v64, v132
	v_sub_f32_e32 v65, v65, v133
	v_mul_f32_e64 v132, |v135|, s54
	v_exp_f32_e32 v132, v132
	v_fma_f32 v130, -v130, s68, v64
	v_fma_f32 v131, -v131, s68, v65
	v_add_f32_e32 v67, 1.0, v132
	v_mov_b32_e32 v146, v130
	v_min_f32_e32 v135, 0, v135
	v_log_f32_e32 v67, v67
	v_mov_b32_e32 v147, v131
	v_mul_f32_e32 v132, 0x3f317217, v67
	v_fma_f32 v132, v67, s86, -v132
	v_fmac_f32_e32 v132, 0x3377d1cf, v67
	v_fmac_f32_e32 v132, 0x3f317217, v67
	s_nop 1
	v_mov_b32_e32 v67, v132
	v_mul_f32_e64 v132, |v139|, s54
	v_sub_f32_e32 v66, v134, v66
	v_sub_f32_e32 v67, v135, v67
	v_exp_f32_e32 v134, v132
	v_fma_f32 v68, -v68, s68, v66
	v_fma_f32 v69, -v69, s68, v67
	v_min_f32_e32 v139, 0, v139
	v_mov_b32_e32 v132, v68
	v_add_f32_e32 v68, 1.0, v134
	v_mov_b32_e32 v133, v69
	v_log_f32_e32 v68, v68
	s_nop 0
	v_mul_f32_e32 v69, 0x3f317217, v68
	v_fma_f32 v69, v68, s86, -v69
	v_fmac_f32_e32 v69, 0x3377d1cf, v68
	v_fmac_f32_e32 v69, 0x3f317217, v68
	s_nop 1
	v_sub_f32_e32 v68, v138, v142
	v_sub_f32_e32 v69, v139, v69
	v_fma_f32 v130, -v136, s68, v68
	v_fma_f32 v131, -v137, s68, v69
	v_mul_f32_e64 v136, |v141|, s54
	v_exp_f32_e32 v136, v136
	v_mov_b32_e32 v142, v130
	v_mov_b32_e32 v143, v131
	v_mul_f32_e32 v134, s68, v72
	v_mul_f32_e32 v135, s68, v73
	v_add_f32_e32 v130, 1.0, v136
	v_mul_f32_e64 v138, |v134|, s54
	v_exp_f32_e32 v138, v138
	v_log_f32_e32 v130, v130
	s_nop 0
	v_mul_f32_e32 v131, 0x3f317217, v130
	v_fma_f32 v131, v130, s86, -v131
	v_fmac_f32_e32 v131, 0x3377d1cf, v130
	v_fmac_f32_e32 v131, 0x3f317217, v130
	v_min_f32_e32 v134, 0, v134
	v_min_f32_e32 v141, 0, v141
	v_add_f32_e32 v136, 1.0, v138
	v_sub_f32_e32 v130, v140, v144
	v_sub_f32_e32 v131, v141, v131
	v_log_f32_e32 v136, v136
	v_mul_f32_e64 v138, |v135|, s54
	v_exp_f32_e32 v138, v138
	v_min_f32_e32 v135, 0, v135
	v_mul_f32_e32 v137, 0x3f317217, v136
	v_fma_f32 v137, v136, s86, -v137
	v_fmac_f32_e32 v137, 0x3377d1cf, v136
	v_fmac_f32_e32 v137, 0x3f317217, v136
	v_mov_b32_e32 v136, v137
	v_add_f32_e32 v137, 1.0, v138
	v_fma_f32 v70, -v70, s68, v130
	v_fma_f32 v71, -v71, s68, v131
	s_nop 0
	v_log_f32_e32 v137, v137
	v_mov_b32_e32 v136, v136
	v_mul_f32_e32 v138, 0x3f317217, v137
	v_fma_f32 v138, v137, s86, -v138
	v_fmac_f32_e32 v138, 0x3377d1cf, v137
	v_fmac_f32_e32 v138, 0x3f317217, v137
	s_nop 0
	v_sub_f32_e32 v134, v134, v136
	v_sub_f32_e32 v135, v135, v138
	v_mul_f32_e32 v136, s68, v74
	v_mul_f32_e32 v137, s68, v75
	v_mul_f32_e64 v139, |v136|, s54
	v_exp_f32_e32 v139, v139
	v_mul_f32_e64 v140, |v137|, s54
	v_exp_f32_e32 v140, v140
	v_add_f32_e32 v138, 1.0, v139
	v_min_f32_e32 v136, 0, v136
	v_min_f32_e32 v137, 0, v137
	v_log_f32_e32 v138, v138
	v_fma_f32 v72, -v72, s68, v134
	v_fma_f32 v73, -v73, s68, v135
	v_mul_f32_e32 v139, 0x3f317217, v138
	v_fma_f32 v139, v138, s86, -v139
	v_fmac_f32_e32 v139, 0x3377d1cf, v138
	v_fmac_f32_e32 v139, 0x3f317217, v138
	v_mov_b32_e32 v138, v139
	v_add_f32_e32 v139, 1.0, v140
	s_nop 1
	v_log_f32_e32 v139, v139
	v_mov_b32_e32 v138, v138
	v_mul_f32_e32 v140, 0x3f317217, v139
	v_fma_f32 v140, v139, s86, -v140
	v_fmac_f32_e32 v140, 0x3377d1cf, v139
	v_fmac_f32_e32 v140, 0x3f317217, v139
	s_nop 1
	v_mov_b32_e32 v139, v140
	v_add_f32_e32 v140, v142, v70
	v_add_f32_e32 v141, v143, v71
	v_mov_b32_e32 v142, v76
	v_mov_b32_e32 v143, v78
	v_mul_f32_e32 v144, s68, v142
	v_mul_f32_e32 v145, s68, v143
	v_sub_f32_e32 v136, v136, v138
	v_sub_f32_e32 v137, v137, v139
	v_mul_f32_e64 v76, |v144|, s54
	v_exp_f32_e32 v78, v76
	v_fma_f32 v74, -v74, s68, v136
	v_fma_f32 v75, -v75, s68, v137
	v_mov_b32_e32 v138, v74
	v_mul_f32_e64 v149, |v145|, s54
	v_mov_b32_e32 v139, v75
	v_add_f32_e32 v74, v146, v132
	v_add_f32_e32 v75, v147, v133
	v_exp_f32_e32 v149, v149
	v_add_f32_e32 v146, v74, v140
	v_add_f32_e32 v147, v75, v141
	v_add_f32_e32 v74, 1.0, v78
	ds_bpermute_b32 v148, v235, v147
	ds_bpermute_b32 v76, v235, v146
	v_log_f32_e32 v75, v74
	s_nop 0
	v_mul_f32_e32 v78, 0x3f317217, v75
	v_add_f32_e32 v164, v72, v73
	v_add_f32_e32 v165, v73, v75
	v_min_f32_e32 v74, 0, v144
	v_fma_f32 v144, v75, s86, -v78
	v_mov_b32_e32 v78, v77
	v_mul_f32_e32 v166, s68, v78
	v_mul_f32_e32 v167, s68, v79
	v_fmac_f32_e32 v144, 0x3377d1cf, v75
	v_mul_f32_e64 v77, |v166|, s54
	v_exp_f32_e32 v77, v77
	v_fmac_f32_e32 v144, 0x3f317217, v75
	v_min_f32_e32 v166, 0, v166
	v_add_f32_e32 v77, 1.0, v77
	v_log_f32_e32 v77, v77
	v_mov_b32_e32 v144, v144
	v_mul_f32_e32 v75, 0x3f317217, v77
	v_fma_f32 v75, v77, s86, -v75
	v_fmac_f32_e32 v75, 0x3377d1cf, v77
	v_fmac_f32_e32 v75, 0x3f317217, v77
	s_nop 1
	v_mov_b32_e32 v168, v75
	v_add_f32_e32 v75, 1.0, v149
	s_nop 0
	v_log_f32_e32 v77, v75
	v_min_f32_e32 v75, 0, v145
	v_mul_f32_e32 v145, 0x3f317217, v77
	v_fma_f32 v145, v77, s86, -v145
	v_fmac_f32_e32 v145, 0x3377d1cf, v77
	v_fmac_f32_e32 v145, 0x3f317217, v77
	s_nop 1
	v_mov_b32_e32 v145, v145
	v_mul_f32_e64 v77, |v167|, s54
	v_exp_f32_e32 v77, v77
	v_sub_f32_e32 v74, v74, v144
	v_sub_f32_e32 v75, v75, v145
	v_min_f32_e32 v167, 0, v167
	v_add_f32_e32 v77, 1.0, v77
	v_log_f32_e32 v77, v77
	v_fma_f32 v142, -v142, s68, v74
	v_fma_f32 v143, -v143, s68, v75
	v_mul_f32_e32 v144, 0x3f317217, v77
	v_fma_f32 v144, v77, s86, -v144
	v_fmac_f32_e32 v144, 0x3377d1cf, v77
	v_fmac_f32_e32 v144, 0x3f317217, v77
	v_mov_b32_e32 v169, v144
	v_sub_f32_e32 v144, v166, v168
	v_sub_f32_e32 v145, v167, v169
	v_fma_f32 v78, -v78, s68, v144
	v_fma_f32 v79, -v79, s68, v145
	v_mov_b32_e32 v167, v79
	v_mov_b32_e32 v168, v132
	v_mov_b32_e32 v166, v78
	v_add_f32_e32 v142, v142, v166
	v_add_f32_e32 v143, v143, v167
	v_add_f32_e32 v170, v138, v139
	v_add_f32_e32 v171, v139, v133
	v_add_f32_e32 v164, v164, v170
	v_add_f32_e32 v165, v142, v143
	ds_bpermute_b32 v149, v235, v165
	ds_bpermute_b32 v77, v235, v164
	v_add_f32_e32 v78, v146, v146
	v_add_f32_e32 v79, v146, v147
	v_mov_b32_e32 v169, v64
	v_mov_b32_e32 v64, v133
	v_add_f32_e32 v132, v164, v165
	v_add_f32_e32 v133, v165, v164
	s_waitcnt lgkmcnt(1)
	v_add_f32_e32 v142, v165, v149
	s_waitcnt lgkmcnt(0)
	v_cndmask_b32_e64 v146, 0, v77, s[10:11]
	v_add_f32_e32 v142, v146, v142
	v_add_f32_e32 v146, v132, v149
	v_add_f32_e32 v147, v147, v132
	v_add_f32_e32 v146, v146, v77
	v_cndmask_b32_e64 v163, 0, v148, s[10:11]
	v_add_f32_e32 v147, v147, v149
	v_add_f32_e32 v146, v163, v146
	v_add_f32_e32 v147, v147, v77
	v_cndmask_b32_e64 v163, 0, v76, s[10:11]
	v_add_f32_e32 v76, v76, v148
	v_add_f32_e32 v77, v77, v149
	v_mov_b32_e32 v78, v80
	v_add_f32_e32 v147, v147, v148
	v_add_f32_e32 v77, v76, v77
	v_add_f32_e32 v76, v76, v76
	v_pk_mov_b32 v[80:81], v[80:81], v[132:133] op_sel:[1,0]
	v_add_f32_e32 v147, v163, v147
	v_add_f32_e32 v78, v78, v80
	v_add_f32_e32 v79, v79, v81
	v_mov_b32_e32 v163, v77
	v_add_f32_e32 v80, v162, v78
	v_add_f32_e32 v81, v163, v79
	v_add_f32_e32 v77, v80, v147
	v_add_f32_e32 v78, v168, v140
	v_add_f32_e32 v79, v169, v77
	v_add_f32_e32 v68, v68, v77
	v_add_f32_e32 v76, v78, v79
	v_mul_f32_e32 v76, 0x3fb8aa3b, v76
	v_exp_f32_e32 v76, v76
	v_add_f32_e32 v66, v66, v77
	v_add_f32_e32 v68, v70, v68
	v_add_f32_e32 v70, v130, v77
	v_mov_b32_e32 v78, v76
	v_add_f32_e32 v77, v80, v146
	v_add_f32_e32 v66, v140, v66
	v_add_f32_e32 v64, v64, v141
	v_add_f32_e32 v65, v65, v77
	v_mul_f32_e32 v66, 0x3fb8aa3b, v66
	v_add_f32_e32 v64, v64, v65
	v_add_f32_e32 v65, v67, v77
	v_exp_f32_e32 v66, v66
	v_add_f32_e32 v65, v141, v65
	v_mul_f32_e32 v64, 0x3fb8aa3b, v64
	v_mul_f32_e32 v65, 0x3fb8aa3b, v65
	v_exp_f32_e32 v64, v64
	v_exp_f32_e32 v65, v65
	v_mov_b32_e32 v79, v66
	v_add_f32_e32 v66, v69, v77
	v_add_f32_e32 v66, v71, v66
	v_mul_f32_e32 v66, 0x3fb8aa3b, v66
	v_mov_b32_e32 v71, v64
	v_mov_b32_e32 v76, v65
	v_add_f32_e32 v171, v80, v142
	v_pk_mov_b32 v[64:65], v[72:73], v[134:135] op_sel:[1,0]
	v_exp_f32_e32 v66, v66
	v_add_f32_e32 v67, v131, v77
	v_add_f32_e32 v64, v64, v170
	v_add_f32_e32 v65, v65, v171
	v_add_f32_e32 v67, 0, v67
	v_add_f32_e32 v64, v64, v65
	v_add_f32_e32 v65, v135, v171
	v_mul_f32_e32 v67, 0x3fb8aa3b, v67
	v_mul_f32_e32 v64, 0x3fb8aa3b, v64
	v_add_f32_e32 v65, v170, v65
	v_exp_f32_e32 v67, v67
	v_exp_f32_e32 v64, v64
	v_mul_f32_e32 v65, 0x3fb8aa3b, v65
	v_add_f32_e32 v70, 0, v70
	v_mov_b32_e32 v77, v66
	v_exp_f32_e32 v140, v65
	v_add_f32_e32 v65, v136, v171
	v_add_f32_e32 v66, v137, v171
	v_mul_f32_e32 v68, 0x3fb8aa3b, v68
	v_mul_f32_e32 v70, 0x3fb8aa3b, v70
	v_add_f32_e32 v65, v139, v65
	v_add_f32_e32 v66, 0, v66
	v_exp_f32_e32 v68, v68
	v_exp_f32_e32 v70, v70
	v_mul_f32_e32 v65, 0x3fb8aa3b, v65
	v_mul_f32_e32 v66, 0x3fb8aa3b, v66
	v_mov_b32_e32 v131, v67
	v_exp_f32_e32 v139, v66
	v_exp_f32_e32 v141, v65
	v_mov_b32_e32 v146, v64
	ds_read_b64_tr_b16 v[64:65], v207 offset:34816
	ds_read_b64_tr_b16 v[66:67], v207 offset:37376
	v_cndmask_b32_e64 v138, 0, v149, s[10:11]
	v_add_f32_e32 v72, v80, v138
	v_mov_b32_e32 v142, v74
	v_mov_b32_e32 v130, v68
	v_add_f32_e32 v68, v72, v142
	v_add_f32_e32 v69, v166, v143
	v_mov_b32_e32 v74, v139
	v_add_f32_e32 v73, v68, v69
	v_cvt_pk_bf16_f32 v68, v78, v79
	v_cvt_pk_bf16_f32 v69, v130, v70
	v_cvt_pk_bf16_f32 v70, v71, v76
	v_cvt_pk_bf16_f32 v71, v77, v131
	ds_read_b64_tr_b16 v[76:77], v207 offset:34880
	ds_read_b64_tr_b16 v[130:131], v207 offset:34944
	ds_read_b64_tr_b16 v[134:135], v207 offset:35008
	ds_read_b64_tr_b16 v[78:79], v207 offset:37440
	ds_read_b64_tr_b16 v[132:133], v207 offset:37504
	ds_read_b64_tr_b16 v[136:137], v207 offset:37568
	s_waitcnt lgkmcnt(6)
	v_mfma_f32_32x32x16_bf16 v[48:63], v[64:67], v[68:71], v[48:63]
	v_mul_f32_e32 v64, 0x3fb8aa3b, v73
	v_exp_f32_e32 v64, v64
	v_add_f32_e32 v65, v72, v75
	v_add_f32_e32 v65, v65, v167
	v_mul_f32_e32 v65, 0x3fb8aa3b, v65
	v_mov_b32_e32 v139, v64
	v_add_f32_e32 v64, v72, v144
	v_exp_f32_e32 v75, v65
	v_add_f32_e32 v65, v72, v145
	v_add_f32_e32 v64, v64, v143
	v_add_f32_e32 v65, 0, v65
	v_mul_f32_e32 v64, 0x3fb8aa3b, v64
	v_mul_f32_e32 v65, 0x3fb8aa3b, v65
	v_exp_f32_e32 v64, v64
	v_exp_f32_e32 v72, v65
	s_waitcnt lgkmcnt(2)
	v_mfma_f32_32x32x16_bf16 v[32:47], v[76:79], v[68:71], v[32:47]
	v_mov_b32_e32 v138, v141
	v_mov_b32_e32 v76, v64
	ds_read_b64_tr_b16 v[64:65], v207 offset:39936
	ds_read_b64_tr_b16 v[66:67], v207 offset:42496
	v_add_f32_e32 v162, v80, v81
	s_mov_b32 s14, 0xc2480000
	s_waitcnt lgkmcnt(3)
	v_mfma_f32_32x32x16_bf16 v[16:31], v[130:133], v[68:71], v[16:31]
	v_cmp_gt_f32_e32 vcc, s14, v162
	s_cmp_eq_u64 vcc, exec
	s_cselect_b64 s[14:15], -1, 0
	s_waitcnt lgkmcnt(2)
	v_mfma_f32_32x32x16_bf16 v[0:15], v[134:137], v[68:71], v[0:15]
	v_cvt_pk_bf16_f32 v68, v146, v140
	v_cvt_pk_bf16_f32 v69, v138, v74
	v_cvt_pk_bf16_f32 v70, v139, v76
	v_cvt_pk_bf16_f32 v71, v75, v72
	ds_read_b64_tr_b16 v[72:73], v207 offset:40000
	ds_read_b64_tr_b16 v[76:77], v207 offset:40064
	ds_read_b64_tr_b16 v[130:131], v207 offset:40128
	ds_read_b64_tr_b16 v[74:75], v207 offset:42560
	ds_read_b64_tr_b16 v[78:79], v207 offset:42624
	ds_read_b64_tr_b16 v[132:133], v207 offset:42688
	s_waitcnt lgkmcnt(6)
	v_mfma_f32_32x32x16_bf16 v[48:63], v[64:67], v[68:71], v[48:63]
	s_waitcnt lgkmcnt(2)
	v_mfma_f32_32x32x16_bf16 v[32:47], v[72:75], v[68:71], v[32:47]
	s_waitcnt lgkmcnt(1)
	v_mfma_f32_32x32x16_bf16 v[16:31], v[76:79], v[68:71], v[16:31]
	s_waitcnt lgkmcnt(0)
	v_mfma_f32_32x32x16_bf16 v[0:15], v[130:133], v[68:71], v[0:15]
	s_branch .LBB0_467
.Lsb_near:
	v_add3_u32 v130, s18, v192, v205
	ds_read_b128 v[64:67], v130 offset:8704
	ds_read_b128 v[132:135], v130 offset:8736
	v_or_b32_e32 v163, s23, v200
	v_add3_u32 v207, s22, v204, v206
	s_waitcnt lgkmcnt(1)
	v_mfma_f32_32x32x16_bf16 v[66:81], v[64:67], v[82:85], 0
	s_waitcnt lgkmcnt(0)
	v_mfma_f32_32x32x16_bf16 v[66:81], v[132:135], v[86:89], v[66:81]
	ds_read_b128 v[132:135], v130 offset:8768
	ds_read_b128 v[136:139], v130 offset:8800
	s_waitcnt lgkmcnt(1)
	v_mfma_f32_32x32x16_bf16 v[66:81], v[132:135], v[90:93], v[66:81]
	s_waitcnt lgkmcnt(0)
	v_mfma_f32_32x32x16_bf16 v[66:81], v[136:139], v[94:97], v[66:81]
	ds_read_b128 v[132:135], v130 offset:8832
	ds_read_b128 v[136:139], v130 offset:8864
	s_waitcnt lgkmcnt(1)
	v_mfma_f32_32x32x16_bf16 v[66:81], v[132:135], v[98:101], v[66:81]
	s_waitcnt lgkmcnt(0)
	v_mfma_f32_32x32x16_bf16 v[66:81], v[136:139], v[102:105], v[66:81]
	ds_read_b128 v[132:135], v130 offset:8896
	ds_read_b128 v[136:139], v130 offset:8928
	ds_read_b128 v[208:211], v130 offset:224
	s_waitcnt lgkmcnt(2)
	v_mfma_f32_32x32x16_bf16 v[66:81], v[132:135], v[106:109], v[66:81]
	s_waitcnt lgkmcnt(1)
	v_mfma_f32_32x32x16_bf16 v[66:81], v[136:139], v[110:113], v[66:81]
	s_nop 11
	v_mov_b32_e32 v64, v66
	v_mov_b32_e32 v65, v68
	v_mov_b32_e32 v68, v67
	v_mul_f32_e32 v132, s68, v64
	v_mul_f32_e32 v133, s68, v65
	v_mov_b32_e32 v66, v70
	v_mul_f32_e32 v134, s68, v68
	v_mul_f32_e32 v135, s68, v69
	v_mul_f32_e64 v70, |v132|, s54
	v_mov_b32_e32 v67, v72
	v_mul_f32_e64 v72, |v134|, s54
	v_exp_f32_e32 v70, v70
	v_mul_f32_e64 v131, |v133|, s54
	v_exp_f32_e32 v72, v72
	v_mul_f32_e64 v138, |v135|, s54
	v_exp_f32_e32 v131, v131
	v_mul_f32_e32 v136, s68, v66
	v_mul_f32_e32 v137, s68, v67
	v_exp_f32_e32 v138, v138
	v_mul_f32_e64 v139, |v136|, s54
	v_add_f32_e32 v70, 1.0, v70
	v_exp_f32_e32 v139, v139
	v_add_f32_e32 v72, 1.0, v72
	v_add_f32_e32 v131, 1.0, v131
	v_add_f32_e32 v138, 1.0, v138
	v_log_f32_e32 v70, v70
	v_add_f32_e32 v139, 1.0, v139
	v_log_f32_e32 v72, v72
	v_log_f32_e32 v131, v131
	v_log_f32_e32 v138, v138
	v_mov_b32_e32 v142, v139
	v_mul_f32_e32 v139, 0x3f317217, v70
	v_mul_f32_e32 v140, 0x3f317217, v72
	v_fma_f32 v139, v70, s86, -v139
	v_mul_f32_e32 v141, 0x3f317217, v131
	v_fma_f32 v140, v72, s86, -v140
	v_fmac_f32_e32 v139, 0x3377d1cf, v70
	v_mul_f32_e32 v143, 0x3f317217, v138
	v_fma_f32 v141, v131, s86, -v141
	v_fmac_f32_e32 v140, 0x3377d1cf, v72
	v_fmac_f32_e32 v139, 0x3f317217, v70
	v_fma_f32 v143, v138, s86, -v143
	v_fmac_f32_e32 v141, 0x3377d1cf, v131
	v_fmac_f32_e32 v140, 0x3f317217, v72
	v_fmac_f32_e32 v143, 0x3377d1cf, v138
	v_fmac_f32_e32 v141, 0x3f317217, v131
	v_fmac_f32_e32 v143, 0x3f317217, v138
	v_min_f32_e32 v132, 0, v132
	v_min_f32_e32 v133, 0, v133
	v_sub_f32_e32 v166, v132, v139
	v_sub_f32_e32 v167, v133, v141
	v_fma_f32 v174, -v64, s68, v166
	v_fma_f32 v175, -v65, s68, v167
	v_log_f32_e32 v65, v142
	v_min_f32_e32 v134, 0, v134
	v_min_f32_e32 v135, 0, v135
	v_sub_f32_e32 v164, v134, v140
	v_sub_f32_e32 v165, v135, v143
	v_mov_b32_e32 v72, v71
	v_fma_f32 v172, -v68, s68, v164
	v_fma_f32 v173, -v69, s68, v165
	v_mul_f32_e32 v68, 0x3f317217, v65
	v_fma_f32 v70, v65, s86, -v68
	v_mul_f32_e32 v68, s68, v72
	v_mul_f32_e32 v69, s68, v73
	v_fmac_f32_e32 v70, 0x3377d1cf, v65
	v_mul_f32_e64 v71, |v68|, s54
	v_exp_f32_e32 v71, v71
	v_fmac_f32_e32 v70, 0x3f317217, v65
	v_mul_f32_e64 v131, |v137|, s54
	v_exp_f32_e32 v131, v131
	v_mov_b32_e32 v65, v70
	v_add_f32_e32 v70, 1.0, v71
	v_mul_f32_e64 v133, |v69|, s54
	v_exp_f32_e32 v133, v133
	v_log_f32_e32 v71, v70
	v_mov_b32_e32 v70, v65
	v_min_f32_e32 v64, 0, v136
	v_mul_f32_e32 v65, 0x3f317217, v71
	v_fma_f32 v65, v71, s86, -v65
	v_fmac_f32_e32 v65, 0x3377d1cf, v71
	v_fmac_f32_e32 v65, 0x3f317217, v71
	v_min_f32_e32 v68, 0, v68
	v_min_f32_e32 v69, 0, v69
	v_add_f32_e32 v71, 1.0, v131
	v_mov_b32_e32 v140, v78
	v_mov_b32_e32 v141, v80
	v_log_f32_e32 v71, v71
	v_mov_b32_e32 v132, v65
	v_min_f32_e32 v65, 0, v137
	v_mul_f32_e32 v131, 0x3f317217, v71
	v_fma_f32 v131, v71, s86, -v131
	v_fmac_f32_e32 v131, 0x3377d1cf, v71
	v_fmac_f32_e32 v131, 0x3f317217, v71
	v_mul_f32_e32 v142, s68, v140
	v_mul_f32_e32 v143, s68, v141
	v_mov_b32_e32 v80, v79
	v_mov_b32_e32 v71, v131
	v_add_f32_e32 v131, 1.0, v133
	v_sub_f32_e32 v168, v64, v70
	v_sub_f32_e32 v169, v65, v71
	v_log_f32_e32 v131, v131
	v_fma_f32 v176, -v66, s68, v168
	v_fma_f32 v177, -v67, s68, v169
	v_mul_f32_e32 v144, s68, v80
	v_mul_f32_e32 v145, s68, v81
	v_mul_f32_e32 v64, 0x3f317217, v131
	v_fma_f32 v70, v131, s86, -v64
	v_mov_b32_e32 v64, v74
	v_mul_f32_e32 v66, s68, v64
	v_mul_f32_e32 v67, s68, v76
	v_fmac_f32_e32 v70, 0x3377d1cf, v131
	v_mul_f32_e64 v71, |v66|, s54
	v_exp_f32_e32 v71, v71
	v_fmac_f32_e32 v70, 0x3f317217, v131
	v_min_f32_e32 v66, 0, v66
	v_mov_b32_e32 v133, v70
	v_add_f32_e32 v70, 1.0, v71
	v_sub_f32_e32 v170, v68, v132
	v_sub_f32_e32 v171, v69, v133
	ds_read_b128 v[132:135], v130 offset:32
	v_log_f32_e32 v70, v70
	v_fma_f32 v178, -v72, s68, v170
	v_fma_f32 v179, -v73, s68, v171
	v_mul_f32_e64 v73, |v67|, s54
	v_exp_f32_e32 v73, v73
	v_mul_f32_e32 v68, 0x3f317217, v70
	v_fma_f32 v71, v70, s86, -v68
	v_mul_f32_e32 v68, s68, v75
	v_mul_f32_e32 v69, s68, v77
	v_fmac_f32_e32 v71, 0x3377d1cf, v70
	v_mul_f32_e64 v72, |v68|, s54
	v_exp_f32_e32 v72, v72
	v_fmac_f32_e32 v71, 0x3f317217, v70
	v_mul_f32_e64 v74, |v69|, s54
	v_exp_f32_e32 v74, v74
	v_mov_b32_e32 v70, v71
	v_add_f32_e32 v71, 1.0, v72
	v_min_f32_e32 v67, 0, v67
	v_min_f32_e32 v68, 0, v68
	v_log_f32_e32 v71, v71
	v_mov_b32_e32 v70, v70
	v_min_f32_e32 v69, 0, v69
	v_mul_f32_e32 v72, 0x3f317217, v71
	v_fma_f32 v72, v71, s86, -v72
	v_fmac_f32_e32 v72, 0x3377d1cf, v71
	v_fmac_f32_e32 v72, 0x3f317217, v71
	s_nop 1
	v_mov_b32_e32 v71, v72
	v_add_f32_e32 v72, 1.0, v73
	s_nop 1
	v_log_f32_e32 v73, v72
	v_mov_b32_e32 v72, v71
	v_mul_f32_e32 v71, 0x3f317217, v73
	v_fma_f32 v71, v73, s86, -v71
	v_fmac_f32_e32 v71, 0x3377d1cf, v73
	v_fmac_f32_e32 v71, 0x3f317217, v73
	s_nop 1
	v_add_f32_e32 v73, 1.0, v74
	v_sub_f32_e32 v180, v66, v70
	v_sub_f32_e32 v181, v67, v71
	v_mul_f32_e64 v70, |v143|, s54
	v_log_f32_e32 v73, v73
	v_fma_f32 v184, -v64, s68, v180
	v_fma_f32 v185, -v76, s68, v181
	v_mul_f32_e64 v65, |v142|, s54
	v_exp_f32_e32 v65, v65
	v_mul_f32_e32 v64, 0x3f317217, v73
	v_fma_f32 v64, v73, s86, -v64
	v_fmac_f32_e32 v64, 0x3377d1cf, v73
	v_fmac_f32_e32 v64, 0x3f317217, v73
	v_exp_f32_e32 v131, v70
	v_mov_b32_e32 v73, v64
	v_add_f32_e32 v64, 1.0, v65
	v_mul_f32_e64 v66, |v144|, s54
	v_exp_f32_e32 v66, v66
	v_log_f32_e32 v64, v64
	v_sub_f32_e32 v182, v68, v72
	v_sub_f32_e32 v183, v69, v73
	v_add_f32_e32 v131, 1.0, v131
	v_fma_f32 v186, -v75, s68, v182
	v_fma_f32 v187, -v77, s68, v183
	v_mul_f32_e32 v65, 0x3f317217, v64
	v_fma_f32 v65, v64, s86, -v65
	v_fmac_f32_e32 v65, 0x3377d1cf, v64
	v_fmac_f32_e32 v65, 0x3f317217, v64
	v_min_f32_e32 v142, 0, v142
	v_min_f32_e32 v143, 0, v143
	v_mov_b32_e32 v64, v65
	v_add_f32_e32 v65, 1.0, v66
	v_min_f32_e32 v144, 0, v144
	v_log_f32_e32 v68, v65
	v_mov_b32_e32 v146, v64
	ds_read_b128 v[64:67], v130
	v_mul_f32_e32 v69, 0x3f317217, v68
	v_fma_f32 v69, v68, s86, -v69
	v_fmac_f32_e32 v69, 0x3377d1cf, v68
	v_fmac_f32_e32 v69, 0x3f317217, v68
	s_nop 0
	v_mov_b32_e32 v147, v69
	s_waitcnt lgkmcnt(0)
	v_mfma_f32_32x32x16_bf16 v[64:79], v[64:67], v[82:85], 0
	v_mov_b32_e32 v148, v147
	s_nop 0
	ds_read_b128 v[136:139], v130 offset:64
	v_log_f32_e32 v131, v131
	v_mfma_f32_32x32x16_bf16 v[64:79], v[132:135], v[86:89], v[64:79]
	v_mul_f32_e32 v132, 0x3f317217, v131
	v_fma_f32 v147, v131, s86, -v132
	ds_read_b128 v[132:135], v130 offset:96
	v_fmac_f32_e32 v147, 0x3377d1cf, v131
	v_fmac_f32_e32 v147, 0x3f317217, v131
	s_waitcnt lgkmcnt(1)
	v_mfma_f32_32x32x16_bf16 v[64:79], v[136:139], v[90:93], v[64:79]
	v_mul_f32_e64 v137, |v145|, s54
	v_exp_f32_e32 v149, v137
	ds_read_b128 v[136:139], v130 offset:128
	s_waitcnt lgkmcnt(1)
	v_mfma_f32_32x32x16_bf16 v[64:79], v[132:135], v[94:97], v[64:79]
	v_add_f32_e32 v131, 1.0, v149
	v_add_f32_e64 v188, v142, -v146
	v_add_f32_e64 v189, v143, -v147
	v_min_f32_e32 v145, 0, v145
	ds_read_b128 v[132:135], v130 offset:160
	s_waitcnt lgkmcnt(1)
	v_mfma_f32_32x32x16_bf16 v[64:79], v[136:139], v[98:101], v[64:79]
	v_log_f32_e32 v131, v131
	v_fma_f32 v212, -v140, s68, v188
	v_fma_f32 v213, -v141, s68, v189
	v_mul_f32_e32 v136, 0x3f317217, v131
	v_fma_f32 v140, v131, s86, -v136
	ds_read_b128 v[136:139], v130 offset:192
	s_waitcnt lgkmcnt(1)
	v_mfma_f32_32x32x16_bf16 v[64:79], v[132:135], v[102:105], v[64:79]
	v_fmac_f32_e32 v140, 0x3377d1cf, v131
	v_fmac_f32_e32 v140, 0x3f317217, v131
	s_nop 0
	s_waitcnt lgkmcnt(0)
	v_mfma_f32_32x32x16_bf16 v[64:79], v[136:139], v[106:109], v[64:79]
	v_add_f32_e64 v190, v144, -v148
	v_add_f32_e64 v191, v145, -v140
	ds_read_b64_tr_b16 v[146:147], v207 offset:45056
	ds_read_b64_tr_b16 v[142:143], v207 offset:45120
	ds_read_b64_tr_b16 v[138:139], v207 offset:45184
	ds_read_b64_tr_b16 v[134:135], v207 offset:45248
	ds_read_b64_tr_b16 v[148:149], v207 offset:47616
	ds_read_b64_tr_b16 v[144:145], v207 offset:47680
	ds_read_b64_tr_b16 v[140:141], v207 offset:47744
	ds_read_b64_tr_b16 v[136:137], v207 offset:47808
	ds_read_b64_tr_b16 v[130:131], v207 offset:50176
	ds_read_b64_tr_b16 v[132:133], v207 offset:52736
	v_fma_f32 v216, -v80, s68, v190
	v_fma_f32 v217, -v81, s68, v191
	v_or_b32_e32 v80, 34, v163
	v_cmp_lt_i32_e64 s[26:27], v80, v153
	v_mfma_f32_32x32x16_bf16 v[64:79], v[208:211], v[110:113], v[64:79]
	v_or_b32_e32 v208, 32, v163
	v_cmp_lt_i32_e64 s[30:31], v208, v152
	v_or_b32_e32 v208, 33, v163
	v_cmp_lt_i32_e64 s[40:41], v208, v152
	v_cndmask_b32_e64 v80, 0, v174, s[30:31]
	v_or_b32_e32 v174, 35, v163
	v_cmp_lt_i32_e64 s[38:39], v174, v153
	v_cndmask_b32_e64 v81, 0, v175, s[26:27]
	v_cndmask_b32_e64 v174, 0, v172, s[40:41]
	v_cndmask_b32_e64 v175, 0, v173, s[38:39]
	v_add_f32_e32 v80, v80, v174
	v_add_f32_e32 v81, v81, v175
	v_or_b32_e32 v208, 40, v163
	v_add_f32_e32 v172, v80, v81
	v_add_f32_e32 v173, v81, v80
	v_cmp_lt_i32_e64 s[22:23], v208, v152
	v_or_b32_e32 v173, 42, v163
	v_cmp_lt_i32_e64 s[18:19], v173, v153
	v_or_b32_e32 v173, 43, v163
	v_or_b32_e32 v208, 41, v163
	v_cmp_lt_i32_e64 s[28:29], v173, v153
	v_or_b32_e32 v173, 50, v163
	v_cmp_lt_i32_e64 s[34:35], v208, v152
	v_or_b32_e32 v208, 48, v163
	v_cmp_lt_i32_e32 vcc, v173, v153
	v_or_b32_e32 v173, 51, v163
	v_cmp_lt_i32_e64 s[42:43], v208, v152
	v_or_b32_e32 v208, 49, v163
	v_cmp_lt_i32_e64 s[16:17], v173, v153
	v_or_b32_e32 v173, 58, v163
	v_cmp_lt_i32_e64 s[44:45], v208, v152
	v_or_b32_e32 v208, 56, v163
	v_cmp_lt_i32_e64 s[14:15], v173, v153
	v_or_b32_e32 v173, 59, v163
	v_or_b32_e32 v210, 57, v163
	v_cmp_lt_i32_e64 s[36:37], v208, v152
	v_cmp_lt_i32_e64 s[20:21], v173, v153
	v_cmp_lt_i32_e64 s[24:25], v210, v152
	v_cndmask_b32_e32 v185, 0, v185, vcc
	v_cndmask_b32_e64 v184, 0, v184, s[42:43]
	v_cndmask_b32_e64 v187, 0, v187, s[16:17]
	v_cndmask_b32_e64 v186, 0, v186, s[44:45]
	v_cndmask_b32_e64 v209, 0, v213, s[14:15]
	v_cndmask_b32_e64 v208, 0, v212, s[36:37]
	v_cndmask_b32_e64 v211, 0, v217, s[20:21]
	v_cndmask_b32_e64 v210, 0, v216, s[24:25]
	v_add_f32_e32 v184, v184, v186
	v_add_f32_e32 v185, v185, v187
	v_add_f32_e32 v208, v208, v210
	v_add_f32_e32 v209, v209, v211
	v_add_f32_e32 v240, v184, v185
	v_add_f32_e32 v241, v185, v184
	v_add_f32_e32 v212, v208, v209
	v_add_f32_e32 v213, v209, v208
	ds_bpermute_b32 v216, v235, v212
	ds_bpermute_b32 v184, v235, v240
	v_cndmask_b32_e64 v177, 0, v177, s[18:19]
	s_waitcnt lgkmcnt(1)
	v_add_f32_e32 v208, v212, v216
	s_waitcnt lgkmcnt(0)
	v_cndmask_b32_e64 v213, 0, v184, s[10:11]
	v_add_f32_e32 v208, v213, v208
	v_add_f32_e32 v245, v162, v208
	v_add_f32_e32 v246, v186, v185
	v_add_f32_e32 v247, v180, v245
	v_add_f32_e32 v182, v182, v245
	v_add_f32_e32 v180, v246, v247
	v_mul_f32_e32 v180, 0x3fb8aa3b, v180
	v_exp_f32_e32 v180, v180
	v_add_f32_e32 v182, v185, v182
	v_mul_f32_e32 v182, 0x3fb8aa3b, v182
	v_cndmask_b32_e64 v176, 0, v176, s[22:23]
	v_cndmask_b32_e64 v179, 0, v179, s[28:29]
	v_cndmask_b32_e64 v178, 0, v178, s[34:35]
	v_exp_f32_e32 v182, v182
	v_add_f32_e32 v176, v176, v178
	v_add_f32_e32 v177, v177, v179
	v_cndmask_b32_e64 v213, 0, v180, s[42:43]
	v_add_f32_e32 v180, v181, v245
	v_add_f32_e32 v242, v176, v177
	v_add_f32_e32 v243, v177, v176
	v_add_f32_e32 v180, v187, v180
	ds_bpermute_b32 v80, v235, v172
	ds_bpermute_b32 v176, v235, v242
	v_mul_f32_e32 v180, 0x3fb8aa3b, v180
	v_cndmask_b32_e64 v215, 0, v182, s[44:45]
	v_exp_f32_e32 v239, v180
	v_add_f32_e32 v180, v183, v245
	v_add_f32_e32 v182, v184, v216
	v_add_f32_e32 v183, v240, v212
	v_add_f32_e32 v180, 0, v180
	v_add_f32_e32 v181, v242, v183
	v_add_f32_e32 v181, v181, v216
	v_add_f32_e32 v181, v181, v184
	v_cndmask_b32_e64 v173, 0, v216, s[10:11]
	s_waitcnt lgkmcnt(1)
	v_cndmask_b32_e64 v208, 0, v80, s[10:11]
	v_mul_f32_e32 v180, 0x3fb8aa3b, v180
	s_waitcnt lgkmcnt(0)
	v_add_f32_e32 v181, v181, v176
	v_exp_f32_e32 v241, v180
	v_add_f32_e32 v180, v162, v173
	v_add_f32_e32 v173, v183, v216
	v_add_f32_e32 v181, v208, v181
	v_cndmask_b32_e64 v186, 0, v176, s[10:11]
	v_add_f32_e32 v173, v173, v184
	v_add_f32_e32 v185, v162, v181
	v_add_f32_e32 v173, v186, v173
	v_add_f32_e32 v164, v164, v185
	v_add_f32_e32 v186, v174, v81
	v_add_f32_e32 v187, v166, v185
	v_add_f32_e32 v81, v81, v164
	v_add_f32_e32 v164, v167, v185
	v_add_f32_e32 v165, v165, v185
	v_add_f32_e32 v166, v186, v187
	v_add_f32_e32 v164, v175, v164
	v_add_f32_e32 v165, 0, v165
	v_mul_f32_e32 v166, 0x3fb8aa3b, v166
	v_mul_f32_e32 v164, 0x3fb8aa3b, v164
	v_mul_f32_e32 v165, 0x3fb8aa3b, v165
	v_exp_f32_e32 v166, v166
	v_exp_f32_e32 v164, v164
	v_exp_f32_e32 v165, v165
	v_cndmask_b32_e64 v174, 0, v166, s[30:31]
	v_cndmask_b32_e64 v175, 0, v164, s[26:27]
	v_cndmask_b32_e64 v181, 0, v165, s[38:39]
	v_add_f32_e32 v165, v162, v173
	v_add_f32_e32 v166, v178, v177
	v_add_f32_e32 v167, v168, v165
	v_mul_f32_e32 v81, 0x3fb8aa3b, v81
	v_add_f32_e32 v164, v166, v167
	v_add_f32_e32 v166, v170, v165
	v_add_f32_e32 v167, v169, v165
	v_add_f32_e32 v165, v171, v165
	v_add_f32_e32 v166, v177, v166
	v_add_f32_e32 v167, v179, v167
	v_add_f32_e32 v165, 0, v165
	v_mul_f32_e32 v164, 0x3fb8aa3b, v164
	v_mul_f32_e32 v166, 0x3fb8aa3b, v166
	v_mul_f32_e32 v167, 0x3fb8aa3b, v167
	v_mul_f32_e32 v165, 0x3fb8aa3b, v165
	v_exp_f32_e32 v81, v81
	v_exp_f32_e32 v164, v164
	v_exp_f32_e32 v166, v166
	v_exp_f32_e32 v167, v167
	v_exp_f32_e32 v165, v165
	v_cndmask_b32_e64 v81, 0, v81, s[40:41]
	v_cndmask_b32_e64 v168, 0, v164, s[22:23]
	v_cndmask_b32_e64 v166, 0, v166, s[34:35]
	v_cndmask_b32_e64 v167, 0, v167, s[18:19]
	v_cndmask_b32_e64 v169, 0, v165, s[28:29]
	v_cvt_pk_bf16_f32 v164, v174, v81
	v_cvt_pk_bf16_f32 v165, v175, v181
	v_cvt_pk_bf16_f32 v166, v168, v166
	v_cvt_pk_bf16_f32 v167, v167, v169
	s_nop 0
	s_nop 0
	v_mfma_f32_32x32x16_bf16 v[48:63], v[146:149], v[164:167], v[48:63]
	v_add_f32_e64 v146, v180, v188
	v_add_f32_e64 v147, v210, v209
	v_add_f32_e32 v81, v146, v147
	v_mul_f32_e32 v81, 0x3fb8aa3b, v81
	v_exp_f32_e32 v81, v81
	v_cndmask_b32_e32 v146, 0, v239, vcc
	v_cndmask_b32_e64 v81, 0, v81, s[36:37]
	v_mfma_f32_32x32x16_bf16 v[32:47], v[142:145], v[164:167], v[32:47]
	v_add_f32_e32 v143, v180, v190
	v_add_f32_e32 v144, v180, v189
	v_add_f32_e32 v143, v143, v209
	v_mul_f32_e32 v143, 0x3fb8aa3b, v143
	v_exp_f32_e32 v143, v143
	v_cndmask_b32_e64 v142, 0, v241, s[16:17]
	v_mfma_f32_32x32x16_bf16 v[16:31], v[138:141], v[164:167], v[16:31]
	v_add_f32_e32 v139, v180, v191
	v_add_f32_e32 v138, v144, v211
	v_add_f32_e32 v139, 0, v139
	v_mul_f32_e32 v138, 0x3fb8aa3b, v138
	v_mul_f32_e32 v139, 0x3fb8aa3b, v139
	v_exp_f32_e32 v138, v138
	v_exp_f32_e32 v139, v139
	v_mfma_f32_32x32x16_bf16 v[0:15], v[134:137], v[164:167], v[0:15]
	v_cndmask_b32_e64 v136, 0, v143, s[24:25]
	v_cndmask_b32_e64 v137, 0, v138, s[14:15]
	v_cndmask_b32_e64 v138, 0, v139, s[20:21]
	v_cvt_pk_bf16_f32 v134, v213, v215
	v_cvt_pk_bf16_f32 v135, v146, v142
	v_cvt_pk_bf16_f32 v136, v81, v136
	v_cvt_pk_bf16_f32 v137, v137, v138
	ds_read_b64_tr_b16 v[138:139], v207 offset:50240
	ds_read_b64_tr_b16 v[142:143], v207 offset:50304
	ds_read_b64_tr_b16 v[146:147], v207 offset:50368
	ds_read_b64_tr_b16 v[140:141], v207 offset:52800
	ds_read_b64_tr_b16 v[144:145], v207 offset:52864
	ds_read_b64_tr_b16 v[148:149], v207 offset:52928
	v_mfma_f32_32x32x16_bf16 v[48:63], v[130:133], v[134:137], v[48:63]
	v_mov_b32_e32 v130, v64
	v_mov_b32_e32 v131, v68
	v_mul_f32_e64 v132, v130, s68
	v_mul_f32_e64 v133, v131, s68
	v_mul_f32_e64 v64, |v132|, s54
	v_exp_f32_e32 v64, v64
	v_add_f32_e32 v80, v80, v176
	v_add_f32_e32 v81, v172, v242
	s_waitcnt lgkmcnt(2)
	v_mfma_f32_32x32x16_bf16 v[32:47], v[138:141], v[134:137], v[32:47]
	v_add_f32_e64 v80, v80, v182
	v_add_f32_e64 v81, v81, v183
	v_add_f32_e32 v64, 1.0, v64
	s_nop 1
	v_log_f32_e32 v138, v64
	v_min_f32_e32 v64, 0, v132
	s_waitcnt lgkmcnt(1)
	v_mfma_f32_32x32x16_bf16 v[16:31], v[142:145], v[134:137], v[16:31]
	v_mul_f32_e64 v143, |v133|, s54
	v_mul_f32_e32 v68, 0x3f317217, v138
	v_fma_f32 v132, v138, s86, -v68
	v_mov_b32_e32 v68, v65
	v_fmac_f32_e32 v132, 0x3377d1cf, v138
	v_fmac_f32_e32 v132, 0x3f317217, v138
	s_waitcnt lgkmcnt(0)
	v_mfma_f32_32x32x16_bf16 v[0:15], v[146:149], v[134:137], v[0:15]
	v_mul_f32_e64 v134, v68, s68
	v_mul_f32_e64 v135, v69, s68
	v_mul_f32_e64 v65, |v134|, s54
	v_exp_f32_e32 v65, v65
	v_mov_b32_e32 v137, v70
	v_exp_f32_e32 v143, v143
	v_min_f32_e32 v134, 0, v134
	v_add_f32_e32 v65, 1.0, v65
	v_add_f32_e32 v143, 1.0, v143
	s_nop 0
	v_log_f32_e32 v65, v65
	s_nop 0
	v_mul_f32_e32 v136, 0x3f317217, v65
	v_fma_f32 v140, v65, s86, -v136
	v_mov_b32_e32 v136, v66
	v_mul_f32_e32 v138, s68, v136
	v_mul_f32_e32 v139, s68, v137
	v_fmac_f32_e32 v140, 0x3377d1cf, v65
	v_mul_f32_e64 v66, |v138|, s54
	v_exp_f32_e32 v66, v66
	v_fmac_f32_e32 v140, 0x3f317217, v65
	v_min_f32_e32 v138, 0, v138
	v_add_f32_e32 v66, 1.0, v66
	v_mov_b32_e32 v65, v140
	s_nop 1
	v_log_f32_e32 v142, v66
	v_mov_b32_e32 v70, v67
	v_mul_f32_e32 v140, s68, v70
	v_mul_f32_e32 v141, s68, v71
	v_mul_f32_e64 v67, |v140|, s54
	v_exp_f32_e32 v67, v67
	v_mov_b32_e32 v66, v65
	v_mul_f32_e32 v65, 0x3f317217, v142
	v_fma_f32 v65, v142, s86, -v65
	v_fmac_f32_e32 v65, 0x3377d1cf, v142
	v_fmac_f32_e32 v65, 0x3f317217, v142
	v_add_f32_e32 v67, 1.0, v67
	v_min_f32_e32 v140, 0, v140
	s_nop 1
	v_log_f32_e32 v67, v67
	v_mov_b32_e32 v142, v65
	v_mul_f32_e32 v65, 0x3f317217, v67
	v_fma_f32 v65, v67, s86, -v65
	v_fmac_f32_e32 v65, 0x3377d1cf, v67
	v_fmac_f32_e32 v65, 0x3f317217, v67
	s_nop 1
	s_nop 0
	v_log_f32_e32 v143, v143
	v_mov_b32_e32 v144, v65
	v_min_f32_e32 v65, 0, v133
	v_or_b32_e32 v67, 8, v163
	v_mul_f32_e32 v133, 0x3f317217, v143
	v_fma_f32 v133, v143, s86, -v133
	v_fmac_f32_e32 v133, 0x3377d1cf, v143
	v_fmac_f32_e32 v133, 0x3f317217, v143
	s_nop 1
	v_sub_f32_e32 v64, v64, v132
	v_sub_f32_e32 v65, v65, v133
	v_mul_f32_e64 v132, |v135|, s54
	v_exp_f32_e32 v132, v132
	v_cmp_lt_i32_e32 vcc, v67, v153
	v_fma_f32 v130, -v130, s68, v64
	v_fma_f32 v131, -v131, s68, v65
	v_cmp_lt_i32_e64 s[14:15], v163, v152
	v_add_f32_e32 v67, 1.0, v132
	s_nop 0
	v_cndmask_b32_e64 v146, 0, v130, s[14:15]
	v_min_f32_e32 v135, 0, v135
	v_log_f32_e32 v67, v67
	v_cndmask_b32_e32 v147, 0, v131, vcc
	v_or_b32_e32 v131, 1, v163
	v_or_b32_e32 v130, 9, v163
	v_mul_f32_e32 v132, 0x3f317217, v67
	v_fma_f32 v132, v67, s86, -v132
	v_fmac_f32_e32 v132, 0x3377d1cf, v67
	v_fmac_f32_e32 v132, 0x3f317217, v67
	s_nop 1
	v_mov_b32_e32 v67, v132
	v_mul_f32_e64 v132, |v139|, s54
	v_sub_f32_e32 v66, v134, v66
	v_sub_f32_e32 v67, v135, v67
	v_exp_f32_e32 v134, v132
	v_fma_f32 v68, -v68, s68, v66
	v_fma_f32 v69, -v69, s68, v67
	v_cmp_lt_i32_e64 s[18:19], v131, v152
	v_cmp_lt_i32_e64 s[16:17], v130, v153
	v_min_f32_e32 v139, 0, v139
	v_cndmask_b32_e64 v132, 0, v68, s[18:19]
	v_add_f32_e32 v68, 1.0, v134
	v_cndmask_b32_e64 v133, 0, v69, s[16:17]
	v_or_b32_e32 v135, 2, v163
	v_log_f32_e32 v68, v68
	v_cmp_lt_i32_e64 s[24:25], v135, v152
	v_or_b32_e32 v134, 10, v163
	v_mul_f32_e32 v69, 0x3f317217, v68
	v_fma_f32 v69, v68, s86, -v69
	v_fmac_f32_e32 v69, 0x3377d1cf, v68
	v_fmac_f32_e32 v69, 0x3f317217, v68
	s_nop 1
	v_sub_f32_e32 v68, v138, v142
	v_sub_f32_e32 v69, v139, v69
	v_cmp_lt_i32_e64 s[22:23], v134, v153
	v_fma_f32 v130, -v136, s68, v68
	v_fma_f32 v131, -v137, s68, v69
	v_mul_f32_e64 v136, |v141|, s54
	v_exp_f32_e32 v136, v136
	v_cndmask_b32_e64 v142, 0, v130, s[24:25]
	v_cndmask_b32_e64 v143, 0, v131, s[22:23]
	v_mul_f32_e32 v134, s68, v72
	v_mul_f32_e32 v135, s68, v73
	v_add_f32_e32 v130, 1.0, v136
	v_mul_f32_e64 v138, |v134|, s54
	v_exp_f32_e32 v138, v138
	v_log_f32_e32 v130, v130
	v_or_b32_e32 v136, 11, v163
	v_or_b32_e32 v137, 3, v163
	v_cmp_lt_i32_e64 s[34:35], v137, v152
	v_mul_f32_e32 v131, 0x3f317217, v130
	v_fma_f32 v131, v130, s86, -v131
	v_fmac_f32_e32 v131, 0x3377d1cf, v130
	v_fmac_f32_e32 v131, 0x3f317217, v130
	v_min_f32_e32 v134, 0, v134
	v_min_f32_e32 v141, 0, v141
	v_cmp_lt_i32_e64 s[26:27], v136, v153
	v_add_f32_e32 v136, 1.0, v138
	v_sub_f32_e32 v130, v140, v144
	v_sub_f32_e32 v131, v141, v131
	v_log_f32_e32 v136, v136
	v_mul_f32_e64 v138, |v135|, s54
	v_exp_f32_e32 v138, v138
	v_min_f32_e32 v135, 0, v135
	v_mul_f32_e32 v137, 0x3f317217, v136
	v_fma_f32 v137, v136, s86, -v137
	v_fmac_f32_e32 v137, 0x3377d1cf, v136
	v_fmac_f32_e32 v137, 0x3f317217, v136
	v_or_b32_e32 v140, 16, v163
	v_cmp_lt_i32_e64 s[36:37], v140, v152
	v_mov_b32_e32 v136, v137
	v_add_f32_e32 v137, 1.0, v138
	v_fma_f32 v70, -v70, s68, v130
	v_fma_f32 v71, -v71, s68, v131
	s_nop 0
	v_log_f32_e32 v137, v137
	v_mov_b32_e32 v136, v136
	v_cndmask_b32_e64 v71, 0, v71, s[26:27]
	v_mul_f32_e32 v138, 0x3f317217, v137
	v_fma_f32 v138, v137, s86, -v138
	v_fmac_f32_e32 v138, 0x3377d1cf, v137
	v_fmac_f32_e32 v138, 0x3f317217, v137
	v_cndmask_b32_e64 v70, 0, v70, s[34:35]
	s_nop 0
	v_sub_f32_e32 v134, v134, v136
	v_sub_f32_e32 v135, v135, v138
	v_mul_f32_e32 v136, s68, v74
	v_mul_f32_e32 v137, s68, v75
	v_or_b32_e32 v138, 17, v163
	v_mul_f32_e64 v139, |v136|, s54
	v_exp_f32_e32 v139, v139
	v_cmp_lt_i32_e64 s[20:21], v138, v153
	v_mul_f32_e64 v140, |v137|, s54
	v_exp_f32_e32 v140, v140
	v_add_f32_e32 v138, 1.0, v139
	v_min_f32_e32 v136, 0, v136
	v_min_f32_e32 v137, 0, v137
	v_log_f32_e32 v138, v138
	v_fma_f32 v72, -v72, s68, v134
	v_fma_f32 v73, -v73, s68, v135
	v_mul_f32_e32 v139, 0x3f317217, v138
	v_fma_f32 v139, v138, s86, -v139
	v_fmac_f32_e32 v139, 0x3377d1cf, v138
	v_fmac_f32_e32 v139, 0x3f317217, v138
	v_cndmask_b32_e64 v73, 0, v73, s[20:21]
	v_cndmask_b32_e64 v72, 0, v72, s[36:37]
	v_mov_b32_e32 v138, v139
	v_add_f32_e32 v139, 1.0, v140
	s_nop 1
	v_log_f32_e32 v139, v139
	v_mov_b32_e32 v138, v138
	v_mul_f32_e32 v140, 0x3f317217, v139
	v_fma_f32 v140, v139, s86, -v140
	v_fmac_f32_e32 v140, 0x3377d1cf, v139
	v_fmac_f32_e32 v140, 0x3f317217, v139
	s_nop 1
	v_mov_b32_e32 v139, v140
	v_or_b32_e32 v140, 18, v163
	v_cmp_lt_i32_e64 s[30:31], v140, v152
	v_add_f32_e32 v140, v142, v70
	v_add_f32_e32 v141, v143, v71
	v_mov_b32_e32 v142, v76
	v_mov_b32_e32 v143, v78
	v_mul_f32_e32 v144, s68, v142
	v_mul_f32_e32 v145, s68, v143
	v_sub_f32_e32 v136, v136, v138
	v_sub_f32_e32 v137, v137, v139
	v_mul_f32_e64 v76, |v144|, s54
	v_exp_f32_e32 v78, v76
	v_or_b32_e32 v138, 19, v163
	v_fma_f32 v74, -v74, s68, v136
	v_fma_f32 v75, -v75, s68, v137
	v_cmp_lt_i32_e64 s[28:29], v138, v153
	v_cndmask_b32_e64 v138, 0, v74, s[30:31]
	v_mul_f32_e64 v149, |v145|, s54
	v_cndmask_b32_e64 v139, 0, v75, s[28:29]
	v_add_f32_e32 v74, v146, v132
	v_add_f32_e32 v75, v147, v133
	v_exp_f32_e32 v149, v149
	v_add_f32_e32 v146, v74, v140
	v_add_f32_e32 v147, v75, v141
	v_add_f32_e32 v74, 1.0, v78
	ds_bpermute_b32 v148, v235, v147
	ds_bpermute_b32 v76, v235, v146
	v_log_f32_e32 v75, v74
	s_nop 0
	v_mul_f32_e32 v78, 0x3f317217, v75
	v_add_f32_e32 v164, v72, v73
	v_add_f32_e32 v165, v73, v75
	v_min_f32_e32 v74, 0, v144
	v_fma_f32 v144, v75, s86, -v78
	v_mov_b32_e32 v78, v77
	v_mul_f32_e32 v166, s68, v78
	v_mul_f32_e32 v167, s68, v79
	v_fmac_f32_e32 v144, 0x3377d1cf, v75
	v_mul_f32_e64 v77, |v166|, s54
	v_exp_f32_e32 v77, v77
	v_fmac_f32_e32 v144, 0x3f317217, v75
	v_min_f32_e32 v166, 0, v166
	v_add_f32_e32 v77, 1.0, v77
	v_or_b32_e32 v165, 24, v163
	v_cmp_lt_i32_e64 s[42:43], v165, v152
	v_log_f32_e32 v77, v77
	v_mov_b32_e32 v144, v144
	v_mul_f32_e32 v75, 0x3f317217, v77
	v_fma_f32 v75, v77, s86, -v75
	v_fmac_f32_e32 v75, 0x3377d1cf, v77
	v_fmac_f32_e32 v75, 0x3f317217, v77
	s_nop 1
	v_mov_b32_e32 v168, v75
	v_add_f32_e32 v75, 1.0, v149
	v_or_b32_e32 v149, 26, v163
	s_nop 0
	v_log_f32_e32 v77, v75
	v_min_f32_e32 v75, 0, v145
	v_mul_f32_e32 v145, 0x3f317217, v77
	v_fma_f32 v145, v77, s86, -v145
	v_fmac_f32_e32 v145, 0x3377d1cf, v77
	v_fmac_f32_e32 v145, 0x3f317217, v77
	s_nop 1
	v_mov_b32_e32 v145, v145
	v_mul_f32_e64 v77, |v167|, s54
	v_exp_f32_e32 v77, v77
	v_sub_f32_e32 v74, v74, v144
	v_sub_f32_e32 v75, v75, v145
	v_min_f32_e32 v167, 0, v167
	v_cmp_lt_i32_e64 s[38:39], v149, v153
	v_add_f32_e32 v77, 1.0, v77
	v_or_b32_e32 v149, 27, v163
	v_or_b32_e32 v163, 25, v163
	v_log_f32_e32 v77, v77
	v_fma_f32 v142, -v142, s68, v74
	v_fma_f32 v143, -v143, s68, v75
	v_mul_f32_e32 v144, 0x3f317217, v77
	v_fma_f32 v144, v77, s86, -v144
	v_fmac_f32_e32 v144, 0x3377d1cf, v77
	v_fmac_f32_e32 v144, 0x3f317217, v77
	v_cndmask_b32_e64 v143, 0, v143, s[38:39]
	v_cndmask_b32_e64 v142, 0, v142, s[42:43]
	v_mov_b32_e32 v169, v144
	v_sub_f32_e32 v144, v166, v168
	v_sub_f32_e32 v145, v167, v169
	v_cmp_lt_i32_e64 s[40:41], v149, v153
	v_fma_f32 v78, -v78, s68, v144
	v_fma_f32 v79, -v79, s68, v145
	v_cmp_lt_i32_e64 s[44:45], v163, v152
	v_cndmask_b32_e64 v167, 0, v79, s[40:41]
	v_mov_b32_e32 v168, v132
	v_cndmask_b32_e64 v166, 0, v78, s[44:45]
	v_add_f32_e32 v142, v142, v166
	v_add_f32_e32 v143, v143, v167
	v_add_f32_e32 v170, v138, v139
	v_add_f32_e32 v171, v139, v133
	v_add_f32_e32 v164, v164, v170
	v_add_f32_e32 v165, v142, v143
	ds_bpermute_b32 v149, v235, v165
	ds_bpermute_b32 v77, v235, v164
	v_add_f32_e32 v78, v146, v146
	v_add_f32_e32 v79, v146, v147
	v_mov_b32_e32 v169, v64
	v_mov_b32_e32 v64, v133
	v_add_f32_e32 v132, v164, v165
	v_add_f32_e32 v133, v165, v164
	s_waitcnt lgkmcnt(1)
	v_add_f32_e32 v142, v165, v149
	s_waitcnt lgkmcnt(0)
	v_cndmask_b32_e64 v146, 0, v77, s[10:11]
	v_add_f32_e32 v142, v146, v142
	v_add_f32_e32 v146, v132, v149
	v_add_f32_e32 v147, v147, v132
	v_add_f32_e32 v146, v146, v77
	v_cndmask_b32_e64 v163, 0, v148, s[10:11]
	v_add_f32_e32 v147, v147, v149
	v_add_f32_e32 v146, v163, v146
	v_add_f32_e32 v147, v147, v77
	v_cndmask_b32_e64 v163, 0, v76, s[10:11]
	v_add_f32_e32 v76, v76, v148
	v_add_f32_e32 v77, v77, v149
	v_mov_b32_e32 v78, v80
	v_add_f32_e32 v147, v147, v148
	v_add_f32_e32 v77, v76, v77
	v_add_f32_e32 v76, v76, v76
	v_pk_mov_b32 v[80:81], v[80:81], v[132:133] op_sel:[1,0]
	v_add_f32_e32 v147, v163, v147
	v_add_f32_e32 v78, v78, v80
	v_add_f32_e32 v79, v79, v81
	v_mov_b32_e32 v163, v77
	v_add_f32_e32 v80, v162, v78
	v_add_f32_e32 v81, v163, v79
	v_add_f32_e32 v77, v80, v147
	v_add_f32_e32 v78, v168, v140
	v_add_f32_e32 v79, v169, v77
	v_add_f32_e32 v68, v68, v77
	v_add_f32_e32 v76, v78, v79
	v_mul_f32_e32 v76, 0x3fb8aa3b, v76
	v_exp_f32_e32 v76, v76
	v_add_f32_e32 v66, v66, v77
	v_add_f32_e32 v68, v70, v68
	v_add_f32_e32 v70, v130, v77
	v_cndmask_b32_e64 v78, 0, v76, s[14:15]
	v_add_f32_e32 v77, v80, v146
	v_add_f32_e32 v66, v140, v66
	v_add_f32_e32 v64, v64, v141
	v_add_f32_e32 v65, v65, v77
	v_mul_f32_e32 v66, 0x3fb8aa3b, v66
	v_add_f32_e32 v64, v64, v65
	v_add_f32_e32 v65, v67, v77
	v_exp_f32_e32 v66, v66
	v_add_f32_e32 v65, v141, v65
	v_mul_f32_e32 v64, 0x3fb8aa3b, v64
	v_mul_f32_e32 v65, 0x3fb8aa3b, v65
	v_exp_f32_e32 v64, v64
	v_exp_f32_e32 v65, v65
	v_cndmask_b32_e64 v79, 0, v66, s[18:19]
	v_add_f32_e32 v66, v69, v77
	v_add_f32_e32 v66, v71, v66
	v_mul_f32_e32 v66, 0x3fb8aa3b, v66
	v_cndmask_b32_e32 v71, 0, v64, vcc
	v_cndmask_b32_e64 v76, 0, v65, s[16:17]
	v_add_f32_e32 v171, v80, v142
	v_pk_mov_b32 v[64:65], v[72:73], v[134:135] op_sel:[1,0]
	v_exp_f32_e32 v66, v66
	v_add_f32_e32 v67, v131, v77
	v_add_f32_e32 v64, v64, v170
	v_add_f32_e32 v65, v65, v171
	v_add_f32_e32 v67, 0, v67
	v_add_f32_e32 v64, v64, v65
	v_add_f32_e32 v65, v135, v171
	v_mul_f32_e32 v67, 0x3fb8aa3b, v67
	v_mul_f32_e32 v64, 0x3fb8aa3b, v64
	v_add_f32_e32 v65, v170, v65
	v_exp_f32_e32 v67, v67
	v_exp_f32_e32 v64, v64
	v_mul_f32_e32 v65, 0x3fb8aa3b, v65
	v_add_f32_e32 v70, 0, v70
	v_cndmask_b32_e64 v77, 0, v66, s[22:23]
	v_exp_f32_e32 v140, v65
	v_add_f32_e32 v65, v136, v171
	v_add_f32_e32 v66, v137, v171
	v_mul_f32_e32 v68, 0x3fb8aa3b, v68
	v_mul_f32_e32 v70, 0x3fb8aa3b, v70
	v_add_f32_e32 v65, v139, v65
	v_add_f32_e32 v66, 0, v66
	v_exp_f32_e32 v68, v68
	v_exp_f32_e32 v70, v70
	v_mul_f32_e32 v65, 0x3fb8aa3b, v65
	v_mul_f32_e32 v66, 0x3fb8aa3b, v66
	v_cndmask_b32_e64 v131, 0, v67, s[26:27]
	v_exp_f32_e32 v139, v66
	v_exp_f32_e32 v141, v65
	v_cndmask_b32_e64 v146, 0, v64, s[36:37]
	ds_read_b64_tr_b16 v[64:65], v207 offset:34816
	ds_read_b64_tr_b16 v[66:67], v207 offset:37376
	v_cndmask_b32_e64 v138, 0, v149, s[10:11]
	v_add_f32_e32 v72, v80, v138
	v_mov_b32_e32 v142, v74
	v_cndmask_b32_e64 v130, 0, v68, s[24:25]
	v_cndmask_b32_e64 v70, 0, v70, s[34:35]
	v_add_f32_e32 v68, v72, v142
	v_add_f32_e32 v69, v166, v143
	v_cndmask_b32_e64 v74, 0, v139, s[28:29]
	v_add_f32_e32 v73, v68, v69
	v_cvt_pk_bf16_f32 v68, v78, v79
	v_cvt_pk_bf16_f32 v69, v130, v70
	v_cvt_pk_bf16_f32 v70, v71, v76
	v_cvt_pk_bf16_f32 v71, v77, v131
	ds_read_b64_tr_b16 v[76:77], v207 offset:34880
	ds_read_b64_tr_b16 v[130:131], v207 offset:34944
	ds_read_b64_tr_b16 v[134:135], v207 offset:35008
	ds_read_b64_tr_b16 v[78:79], v207 offset:37440
	ds_read_b64_tr_b16 v[132:133], v207 offset:37504
	ds_read_b64_tr_b16 v[136:137], v207 offset:37568
	s_waitcnt lgkmcnt(6)
	v_mfma_f32_32x32x16_bf16 v[48:63], v[64:67], v[68:71], v[48:63]
	v_mul_f32_e32 v64, 0x3fb8aa3b, v73
	v_exp_f32_e32 v64, v64
	v_add_f32_e32 v65, v72, v75
	v_add_f32_e32 v65, v65, v167
	v_mul_f32_e32 v65, 0x3fb8aa3b, v65
	v_cndmask_b32_e64 v139, 0, v64, s[42:43]
	v_add_f32_e32 v64, v72, v144
	v_exp_f32_e32 v75, v65
	v_add_f32_e32 v65, v72, v145
	v_add_f32_e32 v64, v64, v143
	v_add_f32_e32 v65, 0, v65
	v_mul_f32_e32 v64, 0x3fb8aa3b, v64
	v_mul_f32_e32 v65, 0x3fb8aa3b, v65
	v_exp_f32_e32 v64, v64
	v_exp_f32_e32 v72, v65
	s_waitcnt lgkmcnt(2)
	v_mfma_f32_32x32x16_bf16 v[32:47], v[76:79], v[68:71], v[32:47]
	v_cndmask_b32_e64 v73, 0, v140, s[20:21]
	v_cndmask_b32_e64 v138, 0, v141, s[30:31]
	v_cndmask_b32_e64 v76, 0, v64, s[44:45]
	v_cndmask_b32_e64 v72, 0, v72, s[40:41]
	ds_read_b64_tr_b16 v[64:65], v207 offset:39936
	ds_read_b64_tr_b16 v[66:67], v207 offset:42496
	v_add_f32_e32 v162, v80, v81
	s_mov_b32 s14, 0xc2480000
	s_waitcnt lgkmcnt(3)
	v_mfma_f32_32x32x16_bf16 v[16:31], v[130:133], v[68:71], v[16:31]
	v_cmp_gt_f32_e32 vcc, s14, v162
	s_cmp_eq_u64 vcc, exec
	s_cselect_b64 s[14:15], -1, 0
	s_waitcnt lgkmcnt(2)
	v_mfma_f32_32x32x16_bf16 v[0:15], v[134:137], v[68:71], v[0:15]
	v_cndmask_b32_e64 v71, 0, v75, s[38:39]
	v_cvt_pk_bf16_f32 v68, v146, v73
	v_cvt_pk_bf16_f32 v69, v138, v74
	v_cvt_pk_bf16_f32 v70, v139, v76
	v_cvt_pk_bf16_f32 v71, v71, v72
	ds_read_b64_tr_b16 v[72:73], v207 offset:40000
	ds_read_b64_tr_b16 v[76:77], v207 offset:40064
	ds_read_b64_tr_b16 v[130:131], v207 offset:40128
	ds_read_b64_tr_b16 v[74:75], v207 offset:42560
	ds_read_b64_tr_b16 v[78:79], v207 offset:42624
	ds_read_b64_tr_b16 v[132:133], v207 offset:42688
	s_waitcnt lgkmcnt(6)
	v_mfma_f32_32x32x16_bf16 v[48:63], v[64:67], v[68:71], v[48:63]
	s_waitcnt lgkmcnt(2)
	v_mfma_f32_32x32x16_bf16 v[32:47], v[72:75], v[68:71], v[32:47]
	s_waitcnt lgkmcnt(1)
	v_mfma_f32_32x32x16_bf16 v[16:31], v[76:79], v[68:71], v[16:31]
	s_waitcnt lgkmcnt(0)
	v_mfma_f32_32x32x16_bf16 v[0:15], v[130:133], v[68:71], v[0:15]
